# weight-conversion tile loops: gain loads issued before the next tile's row loads, counted vmcnt(4) instead of vmcnt(0), nxt->cur register copy moved from the latch to just before the next issue so the
# speedup vs baseline: 1.0062x; 1.0062x over previous
; #define LAS __attribute__((address_space(3)))
; DI unsigned cvt_pk_bf16(float lo, float hi) { unsigned r; asm volatile("v_cvt_pk_bf16_f32 %0, %1, %2" : "=v"(r) : "v"(lo), "v"(hi)); return r; }
; DI int tid_fresh() { int t = threadIdx.x; asm volatile("" : "+v"(t)); return t; }
; DI void convert_tiles(KParams P, LAS unsigned char* lds, int first, int stride, int total) {
;   const int tid = tid_fresh(), kr = tid >> 4, c4 = tid & 15;
;   f32x4 cur[4], nxt[4];
;   int tile = first;
;   CvtJob jb;
;   if (tile < total) { jb = cvt_decode(P, tile);
; #pragma unroll
;     for (int p = 0; p < 2; ++p) { const int k = 64 * p + 2 * kr; cur[2 * p] = __builtin_nontemporal_load((const f32x4*)(jb.src + (size_t)k * jb.ld_src + 4 * c4)); cur[2 * p + 1] = __builtin_nontemporal_load((const f32x4*)(jb.src + (size_t)(k + 1) * jb.ld_src + 4 * c4)); } }
;   int buf = 0;
;   for (; tile < total; tile += stride) {
;     const int ntile = tile + stride;
;     CvtJob nj = jb;
;     if (ntile < total) { nj = cvt_decode(P, ntile);
; #pragma unroll
;       for (int p = 0; p < 2; ++p) { const int k = 64 * p + 2 * kr; nxt[2 * p] = __builtin_nontemporal_load((const f32x4*)(nj.src + (size_t)k * nj.ld_src + 4 * c4)); nxt[2 * p + 1] = __builtin_nontemporal_load((const f32x4*)(nj.src + (size_t)(k + 1) * nj.ld_src + 4 * c4)); } }
;     LAS unsigned char* L = lds + buf * 16896;
; #pragma unroll
;     for (int p = 0; p < 2; ++p) {
;       const int k = 64 * p + 2 * kr;
;       float g0 = 1.f, g1 = 1.f;
;       if (jb.gain) { g0 = jb.gain[k]; g1 = jb.gain[k + 1]; }
; #pragma unroll
;       for (int i = 0; i < 4; ++i) {
;         const int sc = 4 * c4 + i; const int n = jb.perm ? ((sc < 32) ? 2 * sc : 2 * (sc - 32) + 1) : sc;
;         *(LAS unsigned*)(L + n * 264 + k * 2) = cvt_pk_bf16(cur[2 * p][i] * g0, cur[2 * p + 1][i] * g1);
;       }
;     }
;     __syncthreads();
; #pragma unroll
;     for (int i = 0; i < 4; ++i) {
;       const int pc = tid + 512 * i, n = pc >> 5, kc = pc & 31;
;       const u32x2 v = *(const LAS u32x2*)(L + n * 264 + kc * 8);
;       *(u32x2*)(jb.dst + (size_t)n * jb.ld_dst + kc * 4) = v;
;     }
;     buf ^= 1; jb = nj;
; #pragma unroll
;     for (int i = 0; i < 4; ++i) cur[i] = nxt[i];
;   }
.LBB0_221:
	v_lshlrev_b32_e32 v36, 2, v19
	v_or_b32_e32 v47, 1, v36
	v_or_b32_e32 v49, 2, v36
	v_or_b32_e32 v51, 3, v36
	v_add_u32_e32 v28, 0x200, v18
	v_lshlrev_b32_e32 v34, 1, v20
	v_and_b32_e32 v0, 31, v18
	v_lshlrev_b32_e32 v45, 2, v20
	v_lshlrev_b32_e32 v20, 3, v19
	v_lshlrev_b32_e32 v22, 1, v47
	v_lshlrev_b32_e32 v24, 1, v49
	v_lshlrev_b32_e32 v26, 1, v51
	v_ashrrev_i32_e32 v44, 5, v18
	v_ashrrev_i32_e32 v46, 5, v28
	v_add_u32_e32 v28, 0x400, v18
	v_add_u32_e32 v18, 0x600, v18
	v_lshlrev_b32_e32 v43, 3, v0
	v_lshlrev_b32_e32 v0, 2, v0
	v_or_b32_e32 v38, 1, v34
	v_add_u32_e32 v40, 64, v34
	v_add_u32_e32 v42, 0x41, v34
	v_subrev_u32_e32 v21, 63, v20
	v_subrev_u32_e32 v23, 63, v22
	v_subrev_u32_e32 v25, 63, v24
	v_subrev_u32_e32 v27, 63, v26
	s_movk_i32 s8, 0x108
	v_ashrrev_i32_e32 v48, 5, v28
	v_ashrrev_i32_e32 v50, 5, v18
	v_cmp_gt_u32_e32 vcc, 8, v19
	v_mov_b32_e32 v18, 0
	v_ashrrev_i32_e32 v35, 31, v34
	v_ashrrev_i32_e32 v37, 31, v38
	v_ashrrev_i32_e32 v39, 31, v40
	v_ashrrev_i32_e32 v41, 31, v42
	v_lshlrev_b32_e32 v58, 1, v40
	v_mul_lo_u32 v59, v44, s8
	v_mul_lo_u32 v60, v46, s8
	v_mul_lo_u32 v61, v48, s8
	v_mul_lo_u32 v62, v50, s8
	v_cndmask_b32_e32 v63, v21, v20, vcc
	v_cndmask_b32_e32 v64, v23, v22, vcc
	v_cndmask_b32_e32 v65, v25, v24, vcc
	v_cndmask_b32_e32 v66, v27, v26, vcc
	s_mov_b32 s42, 0
	v_lshlrev_b32_e32 v0, 1, v0
	v_readlane_b32 s12, v251, 0
	v_mov_b32_e32 v19, v18
	v_mov_b32_e32 v20, v18
	v_mov_b32_e32 v21, v18
	v_mov_b32_e32 v22, v18
	v_mov_b32_e32 v23, v18
	v_mov_b32_e32 v24, v18
	v_mov_b32_e32 v25, v18
	v_mov_b32_e32 v26, v18
	v_mov_b32_e32 v27, v18
	v_mov_b32_e32 v28, v18
	v_mov_b32_e32 v29, v18
	v_mov_b32_e32 v30, v18
	v_mov_b32_e32 v31, v18
	v_mov_b32_e32 v32, v18
	v_mov_b32_e32 v33, v18
	v_mov_b32_e32 v67, v53
	s_mov_b64 s[14:15], s[4:5]
	s_mov_b32 s44, s33
	s_mov_b64 s[10:11], s[6:7]
	s_mov_b32 s98, 1
	s_branch .LBB0_223
.Lcv0_last:
	s_cmp_lg_u32 s98, 0
	s_cbranch_scc1 .LBB0_281
	s_waitcnt vmcnt(4)
	v_mov_b32_e32 v10, v18
	v_mov_b32_e32 v11, v19
	v_mov_b32_e32 v12, v20
	v_mov_b32_e32 v13, v21
	v_mov_b32_e32 v14, v22
	v_mov_b32_e32 v15, v23
	v_mov_b32_e32 v16, v24
	v_mov_b32_e32 v17, v25
	v_mov_b32_e32 v6, v26
	v_mov_b32_e32 v7, v27
	v_mov_b32_e32 v8, v28
	v_mov_b32_e32 v9, v29
	v_mov_b32_e32 v2, v30
	v_mov_b32_e32 v3, v31
	v_mov_b32_e32 v4, v32
	v_mov_b32_e32 v5, v33
	s_branch .LBB0_281
.LBB0_222:
	v_mul_i32_i24_e32 v13, 0x108, v68
	v_add_u32_e32 v14, s4, v58
	v_mul_f32_e32 v6, v6, v72
	v_mul_f32_e32 v2, v2, v73
	v_cvt_pk_bf16_f32 v2, v6, v2
	v_add_u32_e32 v6, v14, v13
	v_mul_i32_i24_e32 v10, 0x108, v10
	ds_write_b32 v6, v2
	v_mul_f32_e32 v2, v7, v72
	v_mul_f32_e32 v3, v3, v73
	v_cvt_pk_bf16_f32 v2, v2, v3
	v_add_u32_e32 v3, v14, v10
	v_mul_i32_i24_e32 v11, 0x108, v11
	ds_write_b32 v3, v2
	v_mul_f32_e32 v2, v8, v72
	v_mul_f32_e32 v3, v4, v73
	v_cvt_pk_bf16_f32 v2, v2, v3
	v_add_u32_e32 v3, v14, v11
	v_mul_i32_i24_e32 v12, 0x108, v12
	ds_write_b32 v3, v2
	v_mul_f32_e32 v2, v9, v72
	v_mul_f32_e32 v3, v5, v73
	v_add_u32_e32 v8, s4, v43
	v_cvt_pk_bf16_f32 v2, v2, v3
	v_add_u32_e32 v3, v14, v12
	v_add_u32_e32 v4, v8, v59
	ds_write_b32 v3, v2
	s_waitcnt lgkmcnt(0)
	s_barrier
	ds_read_b64 v[4:5], v4
	v_lshl_add_u64 v[2:3], s[6:7], 0, v[0:1]
	v_mad_i64_i32 v[6:7], s[4:5], s33, v44, 0
	v_add_u32_e32 v9, v8, v60
	v_add_u32_e32 v10, v8, v61
	v_add_u32_e32 v12, v8, v62
	v_lshl_add_u64 v[6:7], v[6:7], 1, v[2:3]
	ds_read_b64 v[8:9], v9
	ds_read_b64 v[10:11], v10
	ds_read_b64 v[12:13], v12
	s_waitcnt lgkmcnt(3)
	global_store_dwordx2 v[6:7], v[4:5], off
	v_mad_i64_i32 v[4:5], s[4:5], s33, v46, 0
	v_lshl_add_u64 v[4:5], v[4:5], 1, v[2:3]
	s_waitcnt lgkmcnt(2)
	global_store_dwordx2 v[4:5], v[8:9], off
	v_mad_i64_i32 v[4:5], s[4:5], s33, v48, 0
	v_lshl_add_u64 v[4:5], v[4:5], 1, v[2:3]
	s_waitcnt lgkmcnt(1)
	global_store_dwordx2 v[4:5], v[10:11], off
	v_mad_i64_i32 v[4:5], s[4:5], s33, v50, 0
	v_lshl_add_u64 v[2:3], v[4:5], 1, v[2:3]
	s_waitcnt lgkmcnt(0)
	global_store_dwordx2 v[2:3], v[12:13], off
	s_xor_b32 s42, s42, 1
	s_andn2_b64 vcc, exec, s[8:9]
	s_mov_b32 s12, s43
	s_mov_b64 s[4:5], s[14:15]
	v_mov_b32_e32 v53, v67
	s_mov_b32 s33, s44
	s_mov_b64 s[6:7], s[10:11]
	s_cbranch_vccz .LBB0_285
; #define LAS __attribute__((address_space(3)))
; DI CvtJob cvt_decode(KParams P, int tile) {
;   constexpr int NJ = 11;
;   const int jK[NJ]  = {2048, 768, 512, 2048, 2048, 256, 2048, 2048, 8192, 2048, 8192};
;   const int jNT[NJ] = {69, 24, 32, 32, 64, 64, 32, 128, 32, 128, 32};
;   int j = 0, idx = tile;
; #pragma unroll
;   for (int jj = 0; jj < NJ - 1; ++jj) { const int cnt = (jK[jj] / 128) * jNT[jj]; if (j == jj && idx >= cnt) { idx -= cnt; j = jj + 1; } }
;   int K = 2048;
;   switch (j) { case 1: K = 768; break; case 2: K = 512; break; case 5: K = 256; break; case 8: case 10: K = 8192; break; default: break; }
;   const int nkt = K / 128, kt = idx % nkt, ntile = idx / nkt, k0 = kt * 128, n0 = ntile * 64;
; DI void convert_tiles(KParams P, LAS unsigned char* lds, int first, int stride, int total) {
;     ...
;   for (; tile < total; tile += stride) {
;     const int ntile = tile + stride;
;     CvtJob nj = jb;
;     if (ntile < total) { nj = cvt_decode(P, ntile);
; #pragma unroll
;       for (int p = 0; p < 2; ++p) { const int k = 64 * p + 2 * kr; nxt[2 * p] = __builtin_nontemporal_load((const f32x4*)(nj.src + (size_t)k * nj.ld_src + 4 * c4)); nxt[2 * p + 1] = __builtin_nontemporal_load((const f32x4*)(nj.src + (size_t)(k + 1) * nj.ld_src + 4 * c4)); } }
;     LAS unsigned char* L = lds + buf * 16896;
; #pragma unroll
;     for (int p = 0; p < 2; ++p) {
;       const int k = 64 * p + 2 * kr;
;       float g0 = 1.f, g1 = 1.f;
;       if (jb.gain) { g0 = jb.gain[k]; g1 = jb.gain[k + 1]; }
.LBB0_223:
	v_mov_b32_e32 v70, 1.0
	v_mov_b32_e32 v71, 1.0
	v_mov_b32_e32 v72, 1.0
	v_mov_b32_e32 v73, 1.0
	s_cmp_eq_u64 s[4:5], 0
	s_cbranch_scc1 .Lcv0_ng
	v_lshl_add_u64 v[74:75], v[34:35], 2, s[4:5]
	global_load_dwordx2 v[70:71], v[74:75], off
	global_load_dwordx2 v[72:73], v[74:75], off offset:256
.Lcv0_ng:
	s_add_i32 s43, s12, s3
	s_cmp_ge_i32 s43, s17
	s_cselect_b64 s[8:9], -1, 0
	s_and_b64 vcc, exec, s[8:9]
	s_cbranch_vccnz .Lcv0_last
	s_cmpk_gt_i32 s43, 0x44f
	s_cselect_b64 s[10:11], -1, 0
	s_cmpk_lt_i32 s43, 0x450
	v_cndmask_b32_e64 v76, 0, 1, s[10:11]
	s_cselect_b64 s[10:11], -1, 0
	s_and_b64 s[14:15], s[10:11], exec
	s_cselect_b32 s14, 0, 0xfffffbb0
	s_add_i32 s13, s3, s14
	s_add_i32 s13, s13, s12
	s_cmpk_lt_i32 s13, 0x90
	s_cselect_b64 s[12:13], -1, 0
	s_or_b64 s[10:11], s[10:11], s[12:13]
	s_and_b64 s[12:13], s[10:11], exec
	s_cselect_b32 s15, 0, 0xffffff70
	s_add_i32 s20, s14, s15
	s_add_i32 s12, s43, s20
	s_cmpk_lt_i32 s12, 0x80
	s_cselect_b64 s[12:13], -1, 0
	s_and_b64 s[18:19], s[12:13], exec
	s_cselect_b32 s21, 2, 3
	s_or_b64 s[12:13], s[10:11], s[12:13]
	s_and_b64 s[18:19], s[12:13], exec
	s_cselect_b32 s18, 0, 0xffffff80
	s_add_i32 s19, s20, s18
	s_add_i32 s19, s43, s19
	s_and_b64 s[10:11], s[10:11], exec
	v_readfirstlane_b32 s10, v76
	s_cselect_b32 s21, s10, s21
	s_cmpk_lt_i32 s19, 0x200
	s_cselect_b64 s[10:11], -1, 0
	s_or_b64 s[10:11], s[12:13], s[10:11]
	s_and_b64 s[12:13], s[10:11], exec
	s_cselect_b32 s12, 0, 0xfffffe00
	s_add_i32 s22, s18, s12
	s_add_i32 s12, s20, s22
	s_add_i32 s12, s43, s12
	s_cmpk_lt_i32 s12, 0x400
	s_cselect_b64 s[12:13], -1, 0
	s_and_b64 s[18:19], s[12:13], exec
	s_cselect_b32 s23, 4, 5
	s_or_b64 s[12:13], s[10:11], s[12:13]
	s_and_b64 s[18:19], s[12:13], exec
	s_cselect_b32 s18, 0, 0xfffffc00
	s_add_i32 s18, s22, s18
	s_add_i32 s19, s20, s18
	s_add_i32 s19, s43, s19
	s_and_b64 s[10:11], s[10:11], exec
	s_cselect_b32 s21, s21, s23
	s_cmpk_lt_i32 s19, 0x80
	s_cselect_b64 s[10:11], -1, 0
	s_or_b64 s[10:11], s[12:13], s[10:11]
	s_and_b64 s[12:13], s[10:11], exec
	s_cselect_b32 s12, 0, 0xffffff80
	s_add_i32 s22, s18, s12
	s_add_i32 s12, s20, s22
	s_add_i32 s12, s43, s12
	s_cmpk_lt_i32 s12, 0x200
	s_cselect_b64 s[12:13], -1, 0
	s_and_b64 s[18:19], s[12:13], exec
	s_cselect_b32 s23, 6, 7
	s_or_b64 s[12:13], s[10:11], s[12:13]
	s_and_b64 s[18:19], s[12:13], exec
	s_cselect_b32 s18, 0, 0xfffffe00
	s_add_i32 s18, s22, s18
	s_add_i32 s19, s20, s18
	s_add_i32 s19, s43, s19
	s_and_b64 s[10:11], s[10:11], exec
	s_cselect_b32 s21, s21, s23
	s_cmpk_lt_i32 s19, 0x800
	s_cselect_b64 s[10:11], -1, 0
	s_or_b64 s[10:11], s[12:13], s[10:11]
	s_and_b64 s[12:13], s[10:11], exec
	s_cselect_b32 s12, 0, 0xfffff800
	s_add_i32 s22, s18, s12
	s_add_i32 s12, s20, s22
	s_add_i32 s12, s43, s12
	s_cmpk_lt_i32 s12, 0x800
	s_cselect_b64 s[12:13], -1, 0
	s_and_b64 s[18:19], s[12:13], exec
	s_cselect_b32 s23, 8, 9
	s_or_b64 s[12:13], s[10:11], s[12:13]
	s_and_b64 s[18:19], s[12:13], exec
	s_cselect_b32 s18, 0, 0xfffff800
	s_add_i32 s18, s22, s18
	s_add_i32 s20, s20, s18
	s_add_i32 s19, s43, s20
	s_and_b64 s[10:11], s[10:11], exec
	s_cselect_b32 s20, s21, s23
	s_cmpk_lt_i32 s19, 0x800
	s_cselect_b64 s[10:11], -1, 0
	s_or_b64 s[10:11], s[12:13], s[10:11]
	s_and_b64 s[12:13], s[10:11], exec
	s_cselect_b32 s45, s20, 10
	s_cmp_lt_i32 s45, 5
	s_mov_b64 s[12:13], -1
	s_cbranch_scc1 .LBB0_235
	s_cmp_lt_i32 s45, 8
	s_cbranch_scc1 .LBB0_231
	s_cmp_gt_i32 s45, 9
	s_cbranch_scc1 .LBB0_228
	s_cmp_eq_u32 s45, 8
	s_cselect_b64 s[12:13], -1, 0

; DI CvtJob cvt_decode(KParams P, int tile) {
;     ...
;   const int nkt = K / 128, kt = idx % nkt, ntile = idx / nkt, k0 = kt * 128, n0 = ntile * 64;
;   const float* src; int ld_src; bf16_t* dst; int perm = 0; const float* gain = nullptr;
;   switch (j) {
;     case 0: src = P->w_in + (size_t)k0 * 4416 + n0; ld_src = 4416; dst = P->Wt_in; perm = (ntile == 68) ? 1 : 0; break;
;     case 1: src = P->w_uq + (size_t)k0 * 1536 + n0; ld_src = 1536; dst = P->Wt_uq; perm = ((ntile % 3) == 2) ? 1 : 0; gain = P->q_norm + k0; break;
;     case 2: src = P->w_ukv + (size_t)k0 * 2048 + n0; ld_src = 2048; dst = P->Wt_ukv; gain = P->kv_norm + k0; break;
;     case 3: src = P->w_out + (size_t)k0 * 2048 + n0; ld_src = 2048; dst = P->Wt_out; break;
;     case 4: src = P->rw_in + (size_t)k0 * 4096 + n0; ld_src = 4096; dst = P->Wt_rin; gain = P->norm_mix + DM + k0; break;
;     case 5: { const int pn = n0 >> 8, rr = n0 & 255, blk = pn >> 1, half = pn & 1;
;               src = (rr < 128 ? P->w_a : P->w_x) + (size_t)blk * 65536 + (size_t)k0 * 256 + half * 128 + (rr & 127); ld_src = 256; dst = P->Wt_gate; } break;
;     case 6: src = P->rw_out + (size_t)k0 * 2048 + n0; ld_src = 2048; dst = P->Wt_rout; break;
;     case 7: src = P->w1 + (size_t)2048 * 8192 + (size_t)k0 * 8192 + n0; ld_src = 8192; dst = P->Wt_w1 + (size_t)8192 * 2048; gain = P->norm_mlp + DM + k0; break;
;     case 8: src = P->w2 + (size_t)8192 * 2048 + (size_t)k0 * 2048 + n0; ld_src = 2048; dst = P->Wt_w2 + (size_t)2048 * 8192; break;
;     case 9: src = P->w1 + (size_t)k0 * 8192 + n0; ld_src = 8192; dst = P->Wt_w1; gain = P->norm_mlp + k0; break;
;     default: src = P->w2 + (size_t)k0 * 2048 + n0; ld_src = 2048; dst = P->Wt_w2; break;
;   }
;   CvtJob jb; jb.src = src; jb.ld_src = ld_src; jb.dst = dst + (size_t)n0 * K + k0; jb.ld_dst = K; jb.perm = perm; jb.gain = gain; return jb;
.LBB0_243:
	s_and_b64 s[10:11], s[10:11], exec
	s_cselect_b32 s10, 0, 0xfffff800
	s_lshr_b32 s11, s44, 7
	v_cvt_f32_u32_e32 v76, s11
	s_add_i32 s10, s18, s10
	s_add_i32 s10, s10, s14
	s_sub_i32 s12, 0, s11
	v_rcp_iflag_f32_e32 v76, v76
	s_add_i32 s10, s10, s15
	s_add_i32 s10, s43, s10
	s_abs_i32 s14, s10
	v_mul_f32_e32 v76, 0x4f7ffffe, v76
	v_cvt_u32_f32_e32 v76, v76
	s_ashr_i32 s13, s10, 31
	s_mov_b64 s[40:41], -1
	v_readfirstlane_b32 s15, v76
	s_mul_i32 s12, s12, s15
	s_mul_hi_u32 s12, s15, s12
	s_add_i32 s15, s15, s12
	s_mul_hi_u32 s12, s14, s15
	s_mul_i32 s15, s12, s11
	s_sub_i32 s14, s14, s15
	s_add_i32 s18, s12, 1
	s_sub_i32 s15, s14, s11
	s_cmp_ge_u32 s14, s11
	s_cselect_b32 s12, s18, s12
	s_cselect_b32 s14, s15, s14
	s_add_i32 s15, s12, 1
	s_cmp_ge_u32 s14, s11
	s_cselect_b32 s12, s15, s12
	s_xor_b32 s12, s12, s13
	s_sub_i32 s46, s12, s13
	s_mul_i32 s11, s46, s11
	s_sub_i32 s10, s10, s11
	s_lshl_b32 s10, s10, 7
	s_lshl_b32 s12, s46, 6
	s_cmp_lt_i32 s45, 5
	s_cbranch_scc1 .LBB0_264
	s_cmp_lt_i32 s45, 7
	s_cbranch_scc1 .LBB0_257
	s_cmp_lt_i32 s45, 8
	s_cbranch_scc1 .LBB0_254
	s_cmp_lt_i32 s45, 9
	s_cbranch_scc1 .LBB0_251
	s_cmp_lg_u32 s45, 9
	s_mov_b64 s[14:15], -1
	s_cbranch_scc0 .LBB0_249
	s_load_dwordx2 s[14:15], s[0:1], 0xd0
	s_ashr_i32 s11, s10, 31
	s_lshl_b64 s[18:19], s[10:11], 13
	s_waitcnt lgkmcnt(0)
	s_add_u32 s18, s14, s18
	s_addc_u32 s19, s15, s19
	s_ashr_i32 s13, s12, 31
	s_lshl_b64 s[14:15], s[12:13], 2
	s_add_u32 s20, s18, s14
	s_addc_u32 s21, s19, s15
	s_load_dwordx2 s[18:19], s[0:1], 0x120
	s_mov_b64 s[14:15], 0

; #define LAS __attribute__((address_space(3)))
; DI unsigned cvt_pk_bf16(float lo, float hi) { unsigned r; asm volatile("v_cvt_pk_bf16_f32 %0, %1, %2" : "=v"(r) : "v"(lo), "v"(hi)); return r; }
; DI void convert_tiles(KParams P, LAS unsigned char* lds, int first, int stride, int total) {
;     ...
;     if (ntile < total) { nj = cvt_decode(P, ntile);
; #pragma unroll
;       for (int p = 0; p < 2; ++p) { const int k = 64 * p + 2 * kr; nxt[2 * p] = __builtin_nontemporal_load((const f32x4*)(nj.src + (size_t)k * nj.ld_src + 4 * c4)); nxt[2 * p + 1] = __builtin_nontemporal_load((const f32x4*)(nj.src + (size_t)(k + 1) * nj.ld_src + 4 * c4)); } }
;     LAS unsigned char* L = lds + buf * 16896;
; #pragma unroll
;     for (int p = 0; p < 2; ++p) {
;       const int k = 64 * p + 2 * kr;
;       float g0 = 1.f, g1 = 1.f;
;       if (jb.gain) { g0 = jb.gain[k]; g1 = jb.gain[k + 1]; }
; #pragma unroll
;       for (int i = 0; i < 4; ++i) {
;         const int sc = 4 * c4 + i; const int n = jb.perm ? ((sc < 32) ? 2 * sc : 2 * (sc - 32) + 1) : sc;
;         *(LAS unsigned*)(L + n * 264 + k * 2) = cvt_pk_bf16(cur[2 * p][i] * g0, cur[2 * p + 1][i] * g1);
.LBB0_280:
	s_cmp_lg_u32 s98, 0
	s_cbranch_scc1 .Lcv0_nc
	s_waitcnt vmcnt(4)
	v_mov_b32_e32 v10, v18
	v_mov_b32_e32 v11, v19
	v_mov_b32_e32 v12, v20
	v_mov_b32_e32 v13, v21
	v_mov_b32_e32 v14, v22
	v_mov_b32_e32 v15, v23
	v_mov_b32_e32 v16, v24
	v_mov_b32_e32 v17, v25
	v_mov_b32_e32 v6, v26
	v_mov_b32_e32 v7, v27
	v_mov_b32_e32 v8, v28
	v_mov_b32_e32 v9, v29
	v_mov_b32_e32 v2, v30
	v_mov_b32_e32 v3, v31
	v_mov_b32_e32 v4, v32
	v_mov_b32_e32 v5, v33
.Lcv0_nc:
	s_mov_b32 s98, 0
	v_lshlrev_b32_e32 v18, 2, v36
	v_mov_b32_e32 v19, v1
	v_lshl_add_u64 v[26:27], s[20:21], 0, v[18:19]
	v_mul_lo_u32 v20, s23, v34
	v_mul_lo_u32 v21, s22, v35
	v_mad_u64_u32 v[18:19], s[20:21], s22, v34, 0
	v_mul_lo_u32 v30, s23, v40
	v_mul_lo_u32 v31, s22, v39
	v_mad_u64_u32 v[28:29], s[20:21], s22, v40, 0
	v_add3_u32 v19, v19, v21, v20
	v_mul_lo_u32 v22, s23, v38
	v_mul_lo_u32 v23, s22, v37
	v_mad_u64_u32 v[20:21], s[20:21], s22, v38, 0
	v_add3_u32 v29, v29, v31, v30
	v_mul_lo_u32 v32, s23, v42
	v_mul_lo_u32 v33, s22, v41
	v_mad_u64_u32 v[30:31], s[20:21], s22, v42, 0
	v_add3_u32 v21, v21, v23, v22
	v_add3_u32 v31, v31, v33, v32
	v_lshl_add_u64 v[18:19], v[18:19], 2, v[26:27]
	v_lshl_add_u64 v[22:23], v[20:21], 2, v[26:27]
	v_lshl_add_u64 v[28:29], v[28:29], 2, v[26:27]
	v_lshl_add_u64 v[30:31], v[30:31], 2, v[26:27]
	global_load_dwordx4 v[18:21], v[18:19], off nt
	s_nop 0
	global_load_dwordx4 v[22:25], v[22:23], off nt
	s_nop 0
	global_load_dwordx4 v[26:29], v[28:29], off nt
	s_nop 0
	global_load_dwordx4 v[30:33], v[30:31], off nt
	s_mul_i32 s13, s13, s44
	s_mul_hi_u32 s20, s12, s44
	s_add_i32 s13, s20, s13
	s_mul_i32 s12, s12, s44
	s_lshl_b64 s[12:13], s[12:13], 1
	s_waitcnt lgkmcnt(0)
	s_add_u32 s12, s18, s12
	s_addc_u32 s13, s19, s13
	s_lshl_b64 s[10:11], s[10:11], 1
	s_add_u32 s10, s12, s10
	v_cndmask_b32_e64 v67, 0, 1, s[40:41]
	s_addc_u32 s11, s13, s11
	s_mov_b32 s23, 0x8007000
	s_movk_i32 s40, 0x7000
.LBB0_281:
.LBB0_283:
	s_mul_i32 s4, s42, 0x4200
	s_add_i32 s4, s4, 0
	v_cmp_eq_u32_e32 vcc, 0, v53
	v_add_u32_e32 v69, s4, v45
	s_cmp_lg_u64 s[8:9], 0
	s_cbranch_scc1 .Lcv0_w0
	s_waitcnt vmcnt(4)
	s_branch .Lcv0_w1

; #define LAS __attribute__((address_space(3)))
; DI unsigned cvt_pk_bf16(float lo, float hi) { unsigned r; asm volatile("v_cvt_pk_bf16_f32 %0, %1, %2" : "=v"(r) : "v"(lo), "v"(hi)); return r; }
; DI void convert_tiles(KParams P, LAS unsigned char* lds, int first, int stride, int total) {
;     ...
;     for (int p = 0; p < 2; ++p) {
;       const int k = 64 * p + 2 * kr;
;       float g0 = 1.f, g1 = 1.f;
;       if (jb.gain) { g0 = jb.gain[k]; g1 = jb.gain[k + 1]; }
; #pragma unroll
;       for (int i = 0; i < 4; ++i) {
;         const int sc = 4 * c4 + i; const int n = jb.perm ? ((sc < 32) ? 2 * sc : 2 * (sc - 32) + 1) : sc;
;         *(LAS unsigned*)(L + n * 264 + k * 2) = cvt_pk_bf16(cur[2 * p][i] * g0, cur[2 * p + 1][i] * g1);
;       }
.Lcv0_w1:
	v_mul_f32_e32 v10, v10, v70
	v_cndmask_b32_e32 v68, v63, v36, vcc
	v_mul_f32_e32 v14, v14, v71
	s_movk_i32 s5, 0x108
	v_cvt_pk_bf16_f32 v10, v10, v14
	v_mad_i32_i24 v14, v68, s5, v69
	ds_write_b32 v14, v10
	v_cndmask_b32_e32 v10, v64, v47, vcc
	v_mul_f32_e32 v11, v11, v70
	v_mul_f32_e32 v14, v15, v71
	v_cvt_pk_bf16_f32 v11, v11, v14
	v_mad_i32_i24 v14, v10, s5, v69
	ds_write_b32 v14, v11
	v_cndmask_b32_e32 v11, v65, v49, vcc
	v_mul_f32_e32 v12, v12, v70
	v_mul_f32_e32 v14, v16, v71
	v_cvt_pk_bf16_f32 v12, v12, v14
	v_mad_i32_i24 v14, v11, s5, v69
	ds_write_b32 v14, v12
	v_cndmask_b32_e32 v12, v66, v51, vcc
	v_mul_f32_e32 v13, v13, v70
	v_mul_f32_e32 v14, v17, v71
	v_cvt_pk_bf16_f32 v13, v13, v14
	v_mad_i32_i24 v14, v12, s5, v69
	ds_write_b32 v14, v13
	s_branch .LBB0_222

; #define LAS __attribute__((address_space(3)))
; DI int tid_fresh() { int t = threadIdx.x; asm volatile("" : "+v"(t)); return t; }
; DI void convert_tiles(KParams P, LAS unsigned char* lds, int first, int stride, int total) {
;   const int tid = tid_fresh(), kr = tid >> 4, c4 = tid & 15;
;   f32x4 cur[4], nxt[4];
;   int tile = first;
;   CvtJob jb;
;   if (tile < total) { jb = cvt_decode(P, tile);
; #pragma unroll
;     for (int p = 0; p < 2; ++p) { const int k = 64 * p + 2 * kr; cur[2 * p] = __builtin_nontemporal_load((const f32x4*)(jb.src + (size_t)k * jb.ld_src + 4 * c4)); cur[2 * p + 1] = __builtin_nontemporal_load((const f32x4*)(jb.src + (size_t)(k + 1) * jb.ld_src + 4 * c4)); } }
;   int buf = 0;
.LBB0_1100:
	v_lshlrev_b32_e32 v36, 2, v18
	v_or_b32_e32 v47, 1, v36
	v_or_b32_e32 v49, 2, v36
	v_or_b32_e32 v51, 3, v36
	v_add_u32_e32 v28, 0x200, v19
	v_lshlrev_b32_e32 v34, 1, v20
	v_and_b32_e32 v0, 31, v19
	v_lshlrev_b32_e32 v45, 2, v20
	v_lshlrev_b32_e32 v20, 3, v18
	v_lshlrev_b32_e32 v22, 1, v47
	v_lshlrev_b32_e32 v24, 1, v49
	v_lshlrev_b32_e32 v26, 1, v51
	v_ashrrev_i32_e32 v44, 5, v19
	v_ashrrev_i32_e32 v46, 5, v28
	v_add_u32_e32 v28, 0x400, v19
	v_add_u32_e32 v19, 0x600, v19
	v_lshlrev_b32_e32 v43, 3, v0
	v_lshlrev_b32_e32 v0, 2, v0
	v_or_b32_e32 v38, 1, v34
	v_add_u32_e32 v40, 64, v34
	v_add_u32_e32 v42, 0x41, v34
	v_subrev_u32_e32 v21, 63, v20
	v_subrev_u32_e32 v23, 63, v22
	v_subrev_u32_e32 v25, 63, v24
	v_subrev_u32_e32 v27, 63, v26
	s_movk_i32 s8, 0x108
	v_ashrrev_i32_e32 v48, 5, v28
	v_ashrrev_i32_e32 v50, 5, v19
	v_cmp_gt_u32_e32 vcc, 8, v18
	v_mov_b32_e32 v18, 0
	v_ashrrev_i32_e32 v35, 31, v34
	v_ashrrev_i32_e32 v37, 31, v38
	v_ashrrev_i32_e32 v39, 31, v40
	v_ashrrev_i32_e32 v41, 31, v42
	v_lshlrev_b32_e32 v58, 1, v40
	v_mul_lo_u32 v59, v44, s8
	v_mul_lo_u32 v60, v46, s8
	v_mul_lo_u32 v61, v48, s8
	v_mul_lo_u32 v62, v50, s8
	v_cndmask_b32_e32 v63, v21, v20, vcc
	v_cndmask_b32_e32 v64, v23, v22, vcc
	v_cndmask_b32_e32 v65, v25, v24, vcc
	v_cndmask_b32_e32 v66, v27, v26, vcc
	s_mov_b32 s16, 0
	v_lshlrev_b32_e32 v0, 1, v0
	v_readlane_b32 s17, v250, 10
	v_mov_b32_e32 v19, v18
	v_mov_b32_e32 v20, v18
	v_mov_b32_e32 v21, v18
	v_mov_b32_e32 v22, v18
	v_mov_b32_e32 v23, v18
	v_mov_b32_e32 v24, v18
	v_mov_b32_e32 v25, v18
	v_mov_b32_e32 v26, v18
	v_mov_b32_e32 v27, v18
	v_mov_b32_e32 v28, v18
	v_mov_b32_e32 v29, v18
	v_mov_b32_e32 v30, v18
	v_mov_b32_e32 v31, v18
	v_mov_b32_e32 v32, v18
	v_mov_b32_e32 v33, v18
	v_mov_b32_e32 v67, v53
	s_mov_b64 s[12:13], s[4:5]
	s_mov_b32 s40, s3
	s_mov_b64 s[8:9], s[6:7]
	s_mov_b32 s98, 1
	s_branch .LBB0_1102

; #define LAS __attribute__((address_space(3)))
; DI unsigned cvt_pk_bf16(float lo, float hi) { unsigned r; asm volatile("v_cvt_pk_bf16_f32 %0, %1, %2" : "=v"(r) : "v"(lo), "v"(hi)); return r; }
; DI void convert_tiles(KParams P, LAS unsigned char* lds, int first, int stride, int total) {
;     ...
; #pragma unroll
;     for (int p = 0; p < 2; ++p) {
;       const int k = 64 * p + 2 * kr;
;       float g0 = 1.f, g1 = 1.f;
;       if (jb.gain) { g0 = jb.gain[k]; g1 = jb.gain[k + 1]; }
; #pragma unroll
;       for (int i = 0; i < 4; ++i) {
;         const int sc = 4 * c4 + i; const int n = jb.perm ? ((sc < 32) ? 2 * sc : 2 * (sc - 32) + 1) : sc;
;         *(LAS unsigned*)(L + n * 264 + k * 2) = cvt_pk_bf16(cur[2 * p][i] * g0, cur[2 * p + 1][i] * g1);
;       }
;     }
;     __syncthreads();
; #pragma unroll
;     for (int i = 0; i < 4; ++i) {
;       const int pc = tid + 512 * i, n = pc >> 5, kc = pc & 31;
;       const u32x2 v = *(const LAS u32x2*)(L + n * 264 + kc * 8);
;       *(u32x2*)(jb.dst + (size_t)n * jb.ld_dst + kc * 4) = v;
;     }
;     buf ^= 1; jb = nj;
; #pragma unroll
;     for (int i = 0; i < 4; ++i) cur[i] = nxt[i];
;   }
.LBB0_1101:
	v_mul_i32_i24_e32 v13, 0x108, v68
	v_add_u32_e32 v14, s4, v58
	v_mul_f32_e32 v6, v6, v72
	v_mul_f32_e32 v2, v2, v73
	v_cvt_pk_bf16_f32 v2, v6, v2
	v_add_u32_e32 v6, v14, v13
	v_mul_i32_i24_e32 v10, 0x108, v10
	ds_write_b32 v6, v2
	v_mul_f32_e32 v2, v7, v72
	v_mul_f32_e32 v3, v3, v73
	v_cvt_pk_bf16_f32 v2, v2, v3
	v_add_u32_e32 v3, v14, v10
	v_mul_i32_i24_e32 v11, 0x108, v11
	ds_write_b32 v3, v2
	v_mul_f32_e32 v2, v8, v72
	v_mul_f32_e32 v3, v4, v73
	v_cvt_pk_bf16_f32 v2, v2, v3
	v_add_u32_e32 v3, v14, v11
	v_mul_i32_i24_e32 v12, 0x108, v12
	ds_write_b32 v3, v2
	v_mul_f32_e32 v2, v9, v72
	v_mul_f32_e32 v3, v5, v73
	v_add_u32_e32 v8, s4, v43
	v_cvt_pk_bf16_f32 v2, v2, v3
	v_add_u32_e32 v3, v14, v12
	v_add_u32_e32 v4, v8, v59
	ds_write_b32 v3, v2
	s_waitcnt lgkmcnt(0)
	s_barrier
	ds_read_b64 v[4:5], v4
	v_lshl_add_u64 v[2:3], s[6:7], 0, v[0:1]
	v_mad_i64_i32 v[6:7], s[4:5], s3, v44, 0
	v_add_u32_e32 v9, v8, v60
	v_add_u32_e32 v10, v8, v61
	v_add_u32_e32 v12, v8, v62
	v_lshl_add_u64 v[6:7], v[6:7], 1, v[2:3]
	ds_read_b64 v[8:9], v9
	ds_read_b64 v[10:11], v10
	ds_read_b64 v[12:13], v12
	s_waitcnt lgkmcnt(3)
	global_store_dwordx2 v[6:7], v[4:5], off
	v_mad_i64_i32 v[4:5], s[4:5], s3, v46, 0
	v_lshl_add_u64 v[4:5], v[4:5], 1, v[2:3]
	s_waitcnt lgkmcnt(2)
	global_store_dwordx2 v[4:5], v[8:9], off
	v_mad_i64_i32 v[4:5], s[4:5], s3, v48, 0
	v_lshl_add_u64 v[4:5], v[4:5], 1, v[2:3]
	s_waitcnt lgkmcnt(1)
	global_store_dwordx2 v[4:5], v[10:11], off
	v_mad_i64_i32 v[4:5], s[4:5], s3, v50, 0
	v_lshl_add_u64 v[2:3], v[4:5], 1, v[2:3]
	s_xor_b32 s16, s16, 1
	s_addk_i32 s17, 0x80
	s_waitcnt lgkmcnt(0)
	global_store_dwordx2 v[2:3], v[12:13], off
	s_cmpk_lt_i32 s33, 0x2d60
	s_mov_b64 s[4:5], s[12:13]
	v_mov_b32_e32 v53, v67
	s_mov_b32 s3, s40
	s_mov_b64 s[6:7], s[8:9]
	s_cbranch_scc0 .LBB0_1164

; DI CvtJob cvt_decode(KParams P, int tile) {
;     ...
;   const int jK[NJ]  = {2048, 768, 512, 2048, 2048, 256, 2048, 2048, 8192, 2048, 8192};
;   const int jNT[NJ] = {69, 24, 32, 32, 64, 64, 32, 128, 32, 128, 32};
;   int j = 0, idx = tile;
; #pragma unroll
;   for (int jj = 0; jj < NJ - 1; ++jj) { const int cnt = (jK[jj] / 128) * jNT[jj]; if (j == jj && idx >= cnt) { idx -= cnt; j = jj + 1; } }
;   int K = 2048;
;   switch (j) { case 1: K = 768; break; case 2: K = 512; break; case 5: K = 256; break; case 8: case 10: K = 8192; break; default: break; }
.Lcv1_ng:
	s_add_i32 s33, s17, 0xffffff80
	s_cmpk_gt_i32 s33, 0x2d5f
	s_cbranch_scc1 .Lcv1_last
	s_cmpk_gt_i32 s33, 0x3cf
	s_cselect_b64 s[8:9], -1, 0
	s_cmpk_lt_i32 s33, 0x3d0
	v_cndmask_b32_e64 v76, 0, 1, s[8:9]
	s_cselect_b64 s[8:9], -1, 0
	s_and_b64 s[10:11], s[8:9], exec
	s_cselect_b32 s12, 0, 0xfffffbb0
	s_add_i32 s10, s12, s17
	s_cmpk_lt_i32 s10, 0x90
	s_cselect_b64 s[10:11], -1, 0
	s_or_b64 s[8:9], s[8:9], s[10:11]
	s_and_b64 s[10:11], s[8:9], exec
	s_cselect_b32 s13, 0, 0xffffff70
	s_add_i32 s18, s12, s13
	s_add_i32 s10, s17, s18
	s_cmpk_lt_i32 s10, 0x80
	s_cselect_b64 s[10:11], -1, 0
	s_and_b64 s[14:15], s[10:11], exec
	s_cselect_b32 s19, 2, 3
	s_or_b64 s[10:11], s[8:9], s[10:11]
	s_and_b64 s[14:15], s[10:11], exec
	s_cselect_b32 s14, 0, 0xffffff80
	s_add_i32 s15, s18, s14
	s_add_i32 s15, s17, s15
	s_and_b64 s[8:9], s[8:9], exec
	v_readfirstlane_b32 s8, v76
	s_cselect_b32 s19, s8, s19
	s_cmpk_lt_i32 s15, 0x200
	s_cselect_b64 s[8:9], -1, 0
	s_or_b64 s[8:9], s[10:11], s[8:9]
	s_and_b64 s[10:11], s[8:9], exec
	s_cselect_b32 s10, 0, 0xfffffe00
	s_add_i32 s20, s14, s10
	s_add_i32 s10, s18, s20
	s_add_i32 s10, s17, s10
	s_cmpk_lt_i32 s10, 0x400
	s_cselect_b64 s[10:11], -1, 0
	s_and_b64 s[14:15], s[10:11], exec
	s_cselect_b32 s21, 4, 5
	s_or_b64 s[10:11], s[8:9], s[10:11]
	s_and_b64 s[14:15], s[10:11], exec
	s_cselect_b32 s14, 0, 0xfffffc00
	s_add_i32 s14, s20, s14
	s_add_i32 s15, s18, s14
	s_add_i32 s15, s17, s15
	s_and_b64 s[8:9], s[8:9], exec
	s_cselect_b32 s19, s19, s21
	s_cmpk_lt_i32 s15, 0x80
	s_cselect_b64 s[8:9], -1, 0
	s_or_b64 s[8:9], s[10:11], s[8:9]
	s_and_b64 s[10:11], s[8:9], exec
	s_cselect_b32 s10, 0, 0xffffff80
	s_add_i32 s20, s14, s10
	s_add_i32 s10, s18, s20
	s_add_i32 s10, s17, s10
	s_cmpk_lt_i32 s10, 0x200
	s_cselect_b64 s[10:11], -1, 0
	s_and_b64 s[14:15], s[10:11], exec
	s_cselect_b32 s21, 6, 7
	s_or_b64 s[10:11], s[8:9], s[10:11]
	s_and_b64 s[14:15], s[10:11], exec
	s_cselect_b32 s14, 0, 0xfffffe00
	s_add_i32 s14, s20, s14
	s_add_i32 s15, s18, s14
	s_add_i32 s15, s17, s15
	s_and_b64 s[8:9], s[8:9], exec
	s_cselect_b32 s19, s19, s21
	s_cmpk_lt_i32 s15, 0x800
	s_cselect_b64 s[8:9], -1, 0
	s_or_b64 s[8:9], s[10:11], s[8:9]
	s_and_b64 s[10:11], s[8:9], exec
	s_cselect_b32 s10, 0, 0xfffff800
	s_add_i32 s20, s14, s10
	s_add_i32 s10, s18, s20
	s_add_i32 s10, s17, s10
	s_cmpk_lt_i32 s10, 0x800
	s_cselect_b64 s[10:11], -1, 0
	s_and_b64 s[14:15], s[10:11], exec
	s_cselect_b32 s21, 8, 9
	s_or_b64 s[10:11], s[8:9], s[10:11]
	s_and_b64 s[14:15], s[10:11], exec
	s_cselect_b32 s14, 0, 0xfffff800
	s_add_i32 s14, s20, s14
	s_add_i32 s18, s18, s14
	s_add_i32 s15, s17, s18
	s_and_b64 s[8:9], s[8:9], exec
	s_cselect_b32 s18, s19, s21
	s_cmpk_lt_i32 s15, 0x800
	s_cselect_b64 s[8:9], -1, 0
	s_or_b64 s[8:9], s[10:11], s[8:9]
	s_and_b64 s[10:11], s[8:9], exec
	s_cselect_b32 s41, s18, 10
	s_cmp_lt_i32 s41, 5
	s_mov_b64 s[10:11], -1
	s_cbranch_scc1 .LBB0_1114
	s_cmp_lt_i32 s41, 8
	s_cbranch_scc1 .LBB0_1110
	s_cmp_gt_i32 s41, 9
	s_cbranch_scc1 .LBB0_1107
	s_cmp_eq_u32 s41, 8
	s_cselect_b64 s[10:11], -1, 0

; DI CvtJob cvt_decode(KParams P, int tile) {
;     ...
;   switch (j) { case 1: K = 768; break; case 2: K = 512; break; case 5: K = 256; break; case 8: case 10: K = 8192; break; default: break; }
;   const int nkt = K / 128, kt = idx % nkt, ntile = idx / nkt, k0 = kt * 128, n0 = ntile * 64;
;   const float* src; int ld_src; bf16_t* dst; int perm = 0; const float* gain = nullptr;
;   switch (j) {
;     case 0: src = P->w_in + (size_t)k0 * 4416 + n0; ld_src = 4416; dst = P->Wt_in; perm = (ntile == 68) ? 1 : 0; break;
;     case 1: src = P->w_uq + (size_t)k0 * 1536 + n0; ld_src = 1536; dst = P->Wt_uq; perm = ((ntile % 3) == 2) ? 1 : 0; gain = P->q_norm + k0; break;
;     case 2: src = P->w_ukv + (size_t)k0 * 2048 + n0; ld_src = 2048; dst = P->Wt_ukv; gain = P->kv_norm + k0; break;
;     case 3: src = P->w_out + (size_t)k0 * 2048 + n0; ld_src = 2048; dst = P->Wt_out; break;
;     case 4: src = P->rw_in + (size_t)k0 * 4096 + n0; ld_src = 4096; dst = P->Wt_rin; gain = P->norm_mix + DM + k0; break;
;     case 5: { const int pn = n0 >> 8, rr = n0 & 255, blk = pn >> 1, half = pn & 1;
;               src = (rr < 128 ? P->w_a : P->w_x) + (size_t)blk * 65536 + (size_t)k0 * 256 + half * 128 + (rr & 127); ld_src = 256; dst = P->Wt_gate; } break;
;     case 6: src = P->rw_out + (size_t)k0 * 2048 + n0; ld_src = 2048; dst = P->Wt_rout; break;
;     case 7: src = P->w1 + (size_t)2048 * 8192 + (size_t)k0 * 8192 + n0; ld_src = 8192; dst = P->Wt_w1 + (size_t)8192 * 2048; gain = P->norm_mlp + DM + k0; break;
;     case 8: src = P->w2 + (size_t)8192 * 2048 + (size_t)k0 * 2048 + n0; ld_src = 2048; dst = P->Wt_w2 + (size_t)2048 * 8192; break;
;     case 9: src = P->w1 + (size_t)k0 * 8192 + n0; ld_src = 8192; dst = P->Wt_w1; gain = P->norm_mlp + k0; break;
;     default: src = P->w2 + (size_t)k0 * 2048 + n0; ld_src = 2048; dst = P->Wt_w2; break;
.LBB0_1122:
	s_and_b64 s[8:9], s[8:9], exec
	s_cselect_b32 s8, 0, 0xfffff800
	s_lshr_b32 s9, s40, 7
	v_cvt_f32_u32_e32 v76, s9
	s_add_i32 s8, s14, s8
	s_add_i32 s8, s8, s12
	s_sub_i32 s10, 0, s9
	v_rcp_iflag_f32_e32 v76, v76
	s_add_i32 s8, s8, s13
	s_add_i32 s8, s17, s8
	s_abs_i32 s12, s8
	v_mul_f32_e32 v76, 0x4f7ffffe, v76
	v_cvt_u32_f32_e32 v76, v76
	s_ashr_i32 s11, s8, 31
	s_mov_b64 s[22:23], -1
	v_readfirstlane_b32 s13, v76
	s_mul_i32 s10, s10, s13
	s_mul_hi_u32 s10, s13, s10
	s_add_i32 s13, s13, s10
	s_mul_hi_u32 s10, s12, s13
	s_mul_i32 s13, s10, s9
	s_sub_i32 s12, s12, s13
	s_add_i32 s14, s10, 1
	s_sub_i32 s13, s12, s9
	s_cmp_ge_u32 s12, s9
	s_cselect_b32 s10, s14, s10
	s_cselect_b32 s12, s13, s12
	s_add_i32 s13, s10, 1
	s_cmp_ge_u32 s12, s9
	s_cselect_b32 s10, s13, s10
	s_xor_b32 s10, s10, s11
	s_sub_i32 s42, s10, s11
	s_mul_i32 s9, s42, s9
	s_sub_i32 s8, s8, s9
	s_lshl_b32 s8, s8, 7
	s_lshl_b32 s10, s42, 6
	s_cmp_lt_i32 s41, 5
	s_cbranch_scc1 .LBB0_1143
	s_cmp_lt_i32 s41, 7
	s_cbranch_scc1 .LBB0_1136
	s_cmp_lt_i32 s41, 8
	s_cbranch_scc1 .LBB0_1133
	s_cmp_lt_i32 s41, 9
	s_cbranch_scc1 .LBB0_1130
	s_cmp_lg_u32 s41, 9
	s_mov_b64 s[12:13], -1
	s_cbranch_scc0 .LBB0_1128
	s_load_dwordx2 s[12:13], s[0:1], 0xd0
	s_ashr_i32 s9, s8, 31
	s_lshl_b64 s[14:15], s[8:9], 13
	s_waitcnt lgkmcnt(0)
	s_add_u32 s14, s12, s14
	s_addc_u32 s15, s13, s15
	s_ashr_i32 s11, s10, 31
	s_lshl_b64 s[12:13], s[10:11], 2
	s_add_u32 s18, s14, s12
	s_addc_u32 s19, s15, s13
	s_load_dwordx2 s[14:15], s[0:1], 0x120
	s_mov_b64 s[12:13], 0

; #define LAS __attribute__((address_space(3)))
; DI unsigned cvt_pk_bf16(float lo, float hi) { unsigned r; asm volatile("v_cvt_pk_bf16_f32 %0, %1, %2" : "=v"(r) : "v"(lo), "v"(hi)); return r; }
; DI void convert_tiles(KParams P, LAS unsigned char* lds, int first, int stride, int total) {
;     ...
;     if (ntile < total) { nj = cvt_decode(P, ntile);
; #pragma unroll
;       for (int p = 0; p < 2; ++p) { const int k = 64 * p + 2 * kr; nxt[2 * p] = __builtin_nontemporal_load((const f32x4*)(nj.src + (size_t)k * nj.ld_src + 4 * c4)); nxt[2 * p + 1] = __builtin_nontemporal_load((const f32x4*)(nj.src + (size_t)(k + 1) * nj.ld_src + 4 * c4)); } }
;     LAS unsigned char* L = lds + buf * 16896;
; #pragma unroll
;     for (int p = 0; p < 2; ++p) {
;       const int k = 64 * p + 2 * kr;
;       float g0 = 1.f, g1 = 1.f;
;       if (jb.gain) { g0 = jb.gain[k]; g1 = jb.gain[k + 1]; }
; #pragma unroll
;       for (int i = 0; i < 4; ++i) {
;         const int sc = 4 * c4 + i; const int n = jb.perm ? ((sc < 32) ? 2 * sc : 2 * (sc - 32) + 1) : sc;
;         *(LAS unsigned*)(L + n * 264 + k * 2) = cvt_pk_bf16(cur[2 * p][i] * g0, cur[2 * p + 1][i] * g1);
.Lcv1_nc:
	s_mov_b32 s98, 0
	v_lshlrev_b32_e32 v18, 2, v36
	v_mov_b32_e32 v19, v1
	v_lshl_add_u64 v[26:27], s[18:19], 0, v[18:19]
	v_mul_lo_u32 v20, s21, v34
	v_mul_lo_u32 v21, s20, v35
	v_mad_u64_u32 v[18:19], s[18:19], s20, v34, 0
	v_mul_lo_u32 v30, s21, v40
	v_mul_lo_u32 v31, s20, v39
	v_mad_u64_u32 v[28:29], s[18:19], s20, v40, 0
	v_add3_u32 v19, v19, v21, v20
	v_mul_lo_u32 v22, s21, v38
	v_mul_lo_u32 v23, s20, v37
	v_mad_u64_u32 v[20:21], s[18:19], s20, v38, 0
	v_add3_u32 v29, v29, v31, v30
	v_mul_lo_u32 v32, s21, v42
	v_mul_lo_u32 v33, s20, v41
	v_mad_u64_u32 v[30:31], s[18:19], s20, v42, 0
	v_add3_u32 v21, v21, v23, v22
	v_add3_u32 v31, v31, v33, v32
	v_lshl_add_u64 v[18:19], v[18:19], 2, v[26:27]
	v_lshl_add_u64 v[22:23], v[20:21], 2, v[26:27]
	v_lshl_add_u64 v[28:29], v[28:29], 2, v[26:27]
	v_lshl_add_u64 v[30:31], v[30:31], 2, v[26:27]
	global_load_dwordx4 v[18:21], v[18:19], off nt
	s_nop 0
	global_load_dwordx4 v[22:25], v[22:23], off nt
	s_nop 0
	global_load_dwordx4 v[26:29], v[28:29], off nt
	s_nop 0
	global_load_dwordx4 v[30:33], v[30:31], off nt
	s_mul_i32 s11, s11, s40
	s_mul_hi_u32 s18, s10, s40
	s_add_i32 s11, s18, s11
	s_mul_i32 s10, s10, s40
	s_lshl_b64 s[10:11], s[10:11], 1
	s_waitcnt lgkmcnt(0)
	s_add_u32 s10, s14, s10
	s_addc_u32 s11, s15, s11
	s_lshl_b64 s[8:9], s[8:9], 1
	s_add_u32 s8, s10, s8
	v_cndmask_b32_e64 v67, 0, 1, s[22:23]
	s_addc_u32 s9, s11, s9
.LBB0_1160:
.LBB0_1162:
	s_mul_i32 s4, s16, 0x4200
	s_add_i32 s4, s4, 0
	v_cmp_eq_u32_e32 vcc, 0, v53
	v_add_u32_e32 v69, s4, v45
	s_cmpk_ge_i32 s33, 0x2d60
	s_cbranch_scc1 .Lcv1_w0
	s_waitcnt vmcnt(4)
	s_branch .Lcv1_w1
